# remaps and XCD-local seams taken only when the census finds 8 XCCs x 32 workgroups; otherwise the baseline mapping with full barriers
# baseline (speedup 1.0000x reference)
.LBB0_448:
	s_cmp_lt_i32 s62, 3
	s_cselect_b64 s[4:5], -1, 0
	s_add_u32 s44, s60, 0x16000000
	s_addc_u32 s45, s61, 0
	s_and_b64 s[22:23], s[4:5], s[2:3]
	s_andn2_b64 vcc, exec, s[22:23]
	s_cbranch_vccnz .LBB0_468
	s_cmpk_gt_i32 s33, 0xff
	s_cbranch_scc1 .LBB0_468
	v_lshlrev_b32_e32 v0, 3, v207
	v_mov_b32_e32 v1, 0
	v_and_b32_e32 v6, 32, v207
	v_lshl_add_u64 v[2:3], s[14:15], 0, v[0:1]
	v_cmp_eq_u32_e64 s[2:3], 0, v6
	v_and_b32_e32 v6, 16, v207
	s_movk_i32 s6, 0x2000
	v_cmp_eq_u32_e64 s[4:5], 0, v6
	v_add_co_u32_e32 v6, vcc, s6, v2
	s_movk_i32 s6, 0x4000
	s_nop 0
	v_addc_co_u32_e32 v7, vcc, 0, v3, vcc
	v_add_co_u32_e32 v8, vcc, s6, v2
	s_movk_i32 s6, 0x6000
	s_nop 0
	v_addc_co_u32_e32 v9, vcc, 0, v3, vcc
	global_load_dwordx2 v[38:39], v[6:7], off offset:-4096
	global_load_dwordx2 v[40:41], v[6:7], off
	global_load_dwordx2 v[42:43], v[8:9], off offset:-4096
	global_load_dwordx2 v[44:45], v[8:9], off
	v_add_co_u32_e32 v6, vcc, s6, v2
	s_mov_b32 s6, 0x8000
	s_nop 0
	v_addc_co_u32_e32 v7, vcc, 0, v3, vcc
	v_add_co_u32_e32 v8, vcc, s6, v2
	s_mov_b32 s6, 0xa000
	s_nop 0
	v_addc_co_u32_e32 v9, vcc, 0, v3, vcc
	global_load_dwordx2 v[46:47], v[6:7], off offset:-4096
	global_load_dwordx2 v[48:49], v[6:7], off
	global_load_dwordx2 v[50:51], v[8:9], off offset:-4096
	global_load_dwordx2 v[52:53], v[8:9], off
	v_add_co_u32_e32 v6, vcc, s6, v2
	s_mov_b32 s6, 0xc000
	s_nop 0
	v_addc_co_u32_e32 v7, vcc, 0, v3, vcc
	v_add_co_u32_e32 v8, vcc, s6, v2
	s_mov_b32 s6, 0xe000
	s_nop 0
	v_addc_co_u32_e32 v9, vcc, 0, v3, vcc
	global_load_dwordx2 v[54:55], v[6:7], off offset:-4096
	global_load_dwordx2 v[56:57], v[6:7], off
	global_load_dwordx2 v[58:59], v[8:9], off offset:-4096
	global_load_dwordx2 v[60:61], v[8:9], off
	v_add_co_u32_e32 v6, vcc, s6, v2
	s_mov_b32 s6, 0x10000
	s_nop 0
	v_addc_co_u32_e32 v7, vcc, 0, v3, vcc
	v_add_co_u32_e32 v8, vcc, s6, v2
	s_mov_b32 s6, 0x12000
	s_nop 0
	v_addc_co_u32_e32 v9, vcc, 0, v3, vcc
	global_load_dwordx2 v[62:63], v[6:7], off offset:-4096
	global_load_dwordx2 v[64:65], v[6:7], off
	global_load_dwordx2 v[66:67], v[8:9], off offset:-4096
	global_load_dwordx2 v[68:69], v[8:9], off
	v_add_co_u32_e32 v6, vcc, s6, v2
	s_mov_b32 s6, 0x14000
	s_nop 0
	v_addc_co_u32_e32 v7, vcc, 0, v3, vcc
	v_add_co_u32_e32 v8, vcc, s6, v2
	s_mov_b32 s6, 0x16000
	s_nop 0
	v_addc_co_u32_e32 v9, vcc, 0, v3, vcc
	global_load_dwordx2 v[70:71], v[6:7], off offset:-4096
	global_load_dwordx2 v[72:73], v[6:7], off
	global_load_dwordx2 v[74:75], v[8:9], off offset:-4096
	global_load_dwordx2 v[76:77], v[8:9], off
	v_add_co_u32_e32 v6, vcc, s6, v2
	s_mov_b32 s6, 0x18000
	s_nop 0
	v_addc_co_u32_e32 v7, vcc, 0, v3, vcc
	v_add_co_u32_e32 v8, vcc, s6, v2
	s_mov_b32 s6, 0x1a000
	s_nop 0
	v_addc_co_u32_e32 v9, vcc, 0, v3, vcc
	global_load_dwordx2 v[78:79], v[6:7], off offset:-4096
	global_load_dwordx2 v[80:81], v[6:7], off
	global_load_dwordx2 v[82:83], v[8:9], off offset:-4096
	global_load_dwordx2 v[84:85], v[8:9], off
	v_add_co_u32_e32 v6, vcc, s6, v2
	s_mov_b32 s6, 0x1c000
	s_nop 0
	v_addc_co_u32_e32 v7, vcc, 0, v3, vcc
	v_add_co_u32_e32 v8, vcc, s6, v2
	s_mov_b32 s6, 0x1e000
	s_nop 0
	v_addc_co_u32_e32 v9, vcc, 0, v3, vcc
	v_add_co_u32_e32 v2, vcc, s6, v2
	global_load_dwordx2 v[86:87], v[6:7], off offset:-4096
	global_load_dwordx2 v[88:89], v[6:7], off
	global_load_dwordx2 v[90:91], v[8:9], off offset:-4096
	global_load_dwordx2 v[92:93], v[8:9], off
	v_addc_co_u32_e32 v3, vcc, 0, v3, vcc
	global_load_dwordx2 v[94:95], v[2:3], off offset:-4096
	global_load_dwordx2 v[96:97], v[2:3], off
	global_load_dwordx2 v[98:99], v0, s[14:15]
	global_load_dwordx2 v[100:101], v0, s[16:17]
	global_load_dwordx2 v[102:103], v0, s[20:21]
	global_load_dwordx2 v[104:105], v0, s[18:19]
	v_and_b32_e32 v2, 8, v207
	v_cmp_eq_u32_e64 s[6:7], 0, v2
	v_and_b32_e32 v2, 4, v207
	v_cmp_eq_u32_e64 s[8:9], 0, v2
	v_and_b32_e32 v2, 3, v207
	s_add_i32 s14, 0, 0x20000
	s_add_i32 s15, 0, 0x20200
	v_cmp_eq_u32_e64 s[10:11], 0, v2
	v_and_b32_e32 v2, 0x3c0, v207
	v_and_b32_e32 v3, 60, v207
	v_add_u32_e32 v186, s14, v0
	v_add_u32_e32 v187, s15, v0
	v_lshlrev_b32_e32 v0, 4, v207
	v_add3_u32 v185, s14, v2, v3
	v_and_b32_e32 v2, 0x7f0, v0
	v_and_b32_e32 v0, 0x7f, v207
	v_lshlrev_b32_e32 v0, 4, v0
	v_mov_b32_e32 v5, v1
	v_mov_b32_e32 v3, v1
	v_lshl_add_u64 v[110:111], s[42:43], 0, v[0:1]
	v_add_u32_e32 v1, 0x200, v207
	v_lshrrev_b32_e32 v190, 7, v1
	v_add_u32_e32 v1, 0x600, v207
	v_lshrrev_b32_e32 v192, 7, v1
	v_add_u32_e32 v1, 0xa00, v207
	v_lshrrev_b32_e32 v194, 7, v1
	v_add_u32_e32 v1, 0xe00, v207
	v_lshrrev_b32_e32 v196, 7, v1
	v_mbcnt_lo_u32_b32 v1, -1, 0
	v_mbcnt_hi_u32_b32 v1, -1, v1
	v_lshl_add_u64 v[108:109], s[42:43], 0, v[2:3]
	v_and_b32_e32 v3, 64, v1
	v_add_u32_e32 v188, 0, v2
	v_xor_b32_e32 v2, 32, v1
	v_add_u32_e32 v3, 64, v3
	v_cmp_lt_i32_e32 vcc, v2, v3
	v_lshlrev_b32_e32 v4, 2, v207
	v_lshrrev_b32_e32 v189, 7, v207
	v_cndmask_b32_e32 v2, v1, v2, vcc
	v_lshlrev_b32_e32 v197, 2, v2
	v_xor_b32_e32 v2, 16, v1
	v_cmp_lt_i32_e32 vcc, v2, v3
	v_add_u32_e32 v184, 0, v4
	s_and_b32 s100, s33, 7
	s_lshl_b32 s100, s100, 5
	s_lshr_b32 s99, s33, 3
	s_add_i32 s100, s100, s99
	s_cmp_lg_u32 s101, 0
	s_cselect_b32 s100, s100, s33
	s_lshl_b32 s14, s100, 7
	v_cndmask_b32_e32 v2, v1, v2, vcc
	v_lshlrev_b32_e32 v198, 2, v2
	v_xor_b32_e32 v2, 8, v1
	v_cmp_lt_i32_e32 vcc, v2, v3
	v_lshl_or_b32 v0, v189, 11, v0
	v_lshl_add_u64 v[36:37], s[0:1], 0, v[4:5]
	v_cndmask_b32_e32 v2, v1, v2, vcc
	v_lshlrev_b32_e32 v199, 2, v2
	v_xor_b32_e32 v2, 4, v1
	v_cmp_lt_i32_e32 vcc, v2, v3
	v_cmp_gt_u32_e64 s[12:13], 8, v207
	v_lshl_add_u64 v[106:107], s[44:45], 0, v[4:5]
	v_cndmask_b32_e32 v2, v1, v2, vcc
	v_lshlrev_b32_e32 v200, 2, v2
	v_xor_b32_e32 v2, 2, v1
	v_cmp_lt_i32_e32 vcc, v2, v3
	v_or_b32_e32 v191, 8, v189
	v_or_b32_e32 v193, 16, v189
	v_cndmask_b32_e32 v2, v1, v2, vcc
	v_lshlrev_b32_e32 v201, 2, v2
	v_xor_b32_e32 v2, 1, v1
	v_cmp_lt_i32_e32 vcc, v2, v3
	v_or_b32_e32 v195, 24, v189
	v_add_u32_e32 v203, 0xfffffe00, v207
	v_cndmask_b32_e32 v1, v1, v2, vcc
	v_lshlrev_b32_e32 v202, 2, v1
	s_sub_i32 s38, s14, 30
	s_lshl_b32 s39, s64, 7
	v_add_u32_e32 v204, 0, v0
	s_or_b32 s54, s14, 7
	v_add_u32_e32 v205, 0x800, v184
	s_movk_i32 s55, 0x1cff
	s_mov_b32 s14, 0x3a800000
	s_mov_b32 s65, 0x800000
	s_add_i32 s66, 0, 0x20210
	s_add_i32 s67, 0, 0x20220
	s_add_i32 s70, 0, 0x20230
	s_mov_b32 s71, s100
	s_branch .LBB0_452

.LBB0_571:
	s_cmp_lt_i32 s62, 5
	s_cselect_b64 s[4:5], -1, 0
	s_and_b64 s[4:5], s[4:5], s[2:3]
	s_andn2_b64 vcc, exec, s[4:5]
	s_cbranch_vccnz .LBB0_595
	s_and_b32 s2, s33, 7
	s_lshl_b32 s2, s2, 12
	s_lshr_b32 s98, s33, 3
	s_lshl_b32 s98, s98, 3
	s_add_i32 s2, s2, s98
	s_and_b32 s98, s33, 7
	s_add_i32 s98, s98, 1
	s_lshl_b32 s98, s98, 12
	s_lshl_b32 s99, s33, 3
	s_cmp_lg_u32 s101, 0
	s_cselect_b32 s2, s2, s99
	s_cselect_b32 s98, s98, 0x8000
	v_readlane_b32 s3, v243, 6
	s_add_i32 s12, s3, s2
	s_cmp_ge_i32 s12, s98
	s_cbranch_scc1 .LBB0_595
	v_lshlrev_b32_e32 v16, 4, v206
	global_load_dwordx4 v[0:3], v16, s[40:41]
	global_load_dwordx4 v[4:7], v16, s[40:41] offset:1024
	global_load_dwordx4 v[8:11], v16, s[40:41] offset:2048
	global_load_dwordx4 v[12:15], v16, s[40:41] offset:3072
	v_mbcnt_lo_u32_b32 v16, -1, 0
	v_mbcnt_hi_u32_b32 v16, -1, v16
	v_and_b32_e32 v17, 64, v16
	v_add_u32_e32 v17, 64, v17
	v_xor_b32_e32 v18, 1, v16
	v_cmp_lt_i32_e32 vcc, v18, v17
	s_add_u32 s28, s60, 0x1600000
	s_addc_u32 s29, s61, 0
	v_cndmask_b32_e32 v18, v16, v18, vcc
	v_lshlrev_b32_e32 v136, 2, v18
	v_xor_b32_e32 v18, 2, v16
	v_cmp_lt_i32_e32 vcc, v18, v17
	s_add_u32 s30, s60, 0x1500000
	s_addc_u32 s31, s61, 0
	v_cndmask_b32_e32 v18, v16, v18, vcc
	v_lshlrev_b32_e32 v137, 2, v18
	v_xor_b32_e32 v18, 4, v16
	v_cmp_lt_i32_e32 vcc, v18, v17
	s_lshl_b32 s6, s64, 3
	s_cmp_lg_u32 s101, 0
	s_cselect_b32 s6, 0x100, s6
	v_lshlrev_b32_e32 v64, 3, v206
	v_cndmask_b32_e32 v18, v16, v18, vcc
	v_lshlrev_b32_e32 v138, 2, v18
	v_xor_b32_e32 v18, 8, v16
	v_cmp_lt_i32_e32 vcc, v18, v17
	v_mov_b32_e32 v65, 0
	s_ashr_i32 s7, s6, 31
	v_cndmask_b32_e32 v18, v16, v18, vcc
	v_lshlrev_b32_e32 v139, 2, v18
	v_xor_b32_e32 v18, 16, v16
	v_cmp_lt_i32_e32 vcc, v18, v17
	v_lshl_add_u64 v[66:67], s[42:43], 0, v[64:65]
	v_lshl_add_u64 v[68:69], s[68:69], 0, v[64:65]
	v_cndmask_b32_e32 v18, v16, v18, vcc
	v_lshlrev_b32_e32 v140, 2, v18
	v_xor_b32_e32 v18, 32, v16
	v_cmp_lt_i32_e32 vcc, v18, v17
	v_lshl_add_u64 v[70:71], s[44:45], 0, v[64:65]
	v_cmp_eq_u32_e64 s[2:3], 0, v206
	v_cndmask_b32_e32 v16, v16, v18, vcc
	v_lshlrev_b32_e32 v141, 2, v16
	s_lshl_b32 s34, s64, 4
	s_cmp_lg_u32 s101, 0
	s_cselect_b32 s34, 0x200, s34
	s_mul_i32 s35, s64, 24
	s_cmp_lg_u32 s101, 0
	s_cselect_b32 s35, 0x300, s35
	s_lshl_b64 s[8:9], s[6:7], 2
	v_mov_b32_e32 v142, 0x358637bd
	s_mov_b32 s7, 0x800000
	s_branch .LBB0_576

.LBB0_732:
	s_cmp_lt_i32 s62, 7
	s_cselect_b64 s[4:5], -1, 0
	s_and_b64 s[2:3], s[4:5], s[2:3]
	s_andn2_b64 vcc, exec, s[2:3]
	s_cbranch_vccnz .LBB0_810
	v_lshlrev_b32_e32 v0, 2, v206
	global_load_dword v1, v0, s[50:51]
	global_load_dword v2, v0, s[50:51] offset:256
	global_load_dword v3, v0, s[50:51] offset:512
	global_load_dword v4, v0, s[50:51] offset:768
	v_mbcnt_lo_u32_b32 v0, -1, 0
	v_mbcnt_hi_u32_b32 v0, -1, v0
	v_and_b32_e32 v5, 64, v0
	v_xor_b32_e32 v6, 1, v0
	v_add_u32_e32 v5, 64, v5
	v_cmp_lt_i32_e32 vcc, v6, v5
	v_xor_b32_e32 v7, 2, v0
	v_xor_b32_e32 v8, 4, v0
	v_cndmask_b32_e32 v6, v0, v6, vcc
	v_lshlrev_b32_e32 v6, 2, v6
	v_cmp_lt_i32_e32 vcc, v7, v5
	v_xor_b32_e32 v9, 8, v0
	v_xor_b32_e32 v10, 16, v0
	v_cndmask_b32_e32 v7, v0, v7, vcc
	v_lshlrev_b32_e32 v7, 2, v7
	v_cmp_lt_i32_e32 vcc, v8, v5
	v_xor_b32_e32 v11, 32, v0
	s_cmpk_gt_i32 s33, 0xff
	s_mov_b32 s47, 0
	s_waitcnt vmcnt(0)
	v_mul_f32_e32 v12, v1, v2
	ds_bpermute_b32 v12, v6, v12
	v_mul_f32_e32 v13, v3, v4
	ds_bpermute_b32 v6, v6, v13
	s_waitcnt lgkmcnt(1)
	v_fmac_f32_e32 v12, v1, v2
	ds_bpermute_b32 v1, v7, v12
	s_waitcnt lgkmcnt(1)
	v_fmac_f32_e32 v6, v3, v4
	ds_bpermute_b32 v2, v7, v6
	v_cndmask_b32_e32 v3, v0, v8, vcc
	v_lshlrev_b32_e32 v3, 2, v3
	s_waitcnt lgkmcnt(1)
	v_add_f32_e32 v1, v12, v1
	ds_bpermute_b32 v4, v3, v1
	s_waitcnt lgkmcnt(1)
	v_add_f32_e32 v2, v6, v2
	ds_bpermute_b32 v3, v3, v2
	v_cmp_lt_i32_e32 vcc, v9, v5
	s_waitcnt lgkmcnt(1)
	v_add_f32_e32 v1, v1, v4
	v_cndmask_b32_e32 v6, v0, v9, vcc
	v_lshlrev_b32_e32 v6, 2, v6
	s_waitcnt lgkmcnt(0)
	v_add_f32_e32 v2, v2, v3
	ds_bpermute_b32 v3, v6, v1
	ds_bpermute_b32 v4, v6, v2
	v_cmp_lt_i32_e32 vcc, v10, v5
	s_waitcnt lgkmcnt(1)
	v_add_f32_e32 v1, v1, v3
	v_cndmask_b32_e32 v6, v0, v10, vcc
	v_lshlrev_b32_e32 v6, 2, v6
	s_waitcnt lgkmcnt(0)
	v_add_f32_e32 v3, v2, v4
	ds_bpermute_b32 v2, v6, v1
	ds_bpermute_b32 v4, v6, v3
	v_cmp_lt_i32_e32 vcc, v11, v5
	s_waitcnt lgkmcnt(1)
	v_add_f32_e32 v2, v1, v2
	v_cndmask_b32_e32 v0, v0, v11, vcc
	v_lshlrev_b32_e32 v5, 2, v0
	s_waitcnt lgkmcnt(0)
	v_add_f32_e32 v0, v3, v4
	ds_bpermute_b32 v3, v5, v2
	ds_bpermute_b32 v1, v5, v0
	s_cbranch_scc1 .LBB0_810
	v_writelane_b32 v243, s2, 7
	s_waitcnt lgkmcnt(1)
	v_add_f32_e32 v2, v2, v3
	v_mul_f32_e32 v3, 0x3fb8aa3b, v2
	v_writelane_b32 v243, s3, 8
	s_mov_b32 s2, 0x3fb8aa3b
	v_fma_f32 v4, v2, s2, -v3
	v_rndne_f32_e32 v5, v3
	v_fmac_f32_e32 v4, 0x32a5705f, v2
	v_sub_f32_e32 v3, v3, v5
	v_add_f32_e32 v3, v3, v4
	v_exp_f32_e32 v3, v3
	v_cvt_i32_f32_e32 v4, v5
	s_waitcnt lgkmcnt(0)
	v_add_f32_e32 v0, v0, v1
	s_mov_b32 s3, 0xc2ce8ed0
	v_cmp_ngt_f32_e32 vcc, s3, v2
	v_ldexp_f32 v1, v3, v4
	v_mul_f32_e32 v3, 0x3fb8aa3b, v0
	v_fma_f32 v4, v0, s2, -v3
	v_rndne_f32_e32 v5, v3
	v_fmac_f32_e32 v4, 0x32a5705f, v0
	v_sub_f32_e32 v3, v3, v5
	v_add_f32_e32 v3, v3, v4
	v_exp_f32_e32 v3, v3
	v_cvt_i32_f32_e32 v4, v5
	s_mov_b32 s4, 0x42b17218
	v_cndmask_b32_e32 v1, 0, v1, vcc
	v_mov_b32_e32 v5, 0x7f800000
	v_cmp_nlt_f32_e32 vcc, s4, v2
	v_ldexp_f32 v2, v3, v4
	v_lshrrev_b32_e32 v3, 1, v207
	v_cndmask_b32_e32 v1, v5, v1, vcc
	v_cmp_ngt_f32_e32 vcc, s3, v0
	v_and_b32_e32 v3, 4, v3
	v_lshrrev_b32_e32 v210, 5, v206
	v_cndmask_b32_e32 v2, 0, v2, vcc
	v_cmp_nlt_f32_e32 vcc, s4, v0
	v_lshlrev_b32_e32 v176, 4, v210
	v_mov_b32_e32 v177, 0
	v_cndmask_b32_e32 v0, v5, v2, vcc
	v_lshlrev_b32_e32 v2, 1, v207
	v_sub_f32_e32 v0, v1, v0
	v_and_b32_e32 v1, 19, v207
	v_and_b32_e32 v2, 8, v2
	v_or3_b32 v1, v2, v1, v3
	v_lshlrev_b32_e32 v2, 8, v1
	v_bitop3_b32 v1, v1, v210, 15 bitop3:0x6c
	v_lshl_add_u64 v[178:179], s[0:1], 0, v[176:177]
	v_lshlrev_b32_e32 v1, 4, v1
	s_movk_i32 s0, 0x60
	v_bitop3_b32 v6, v1, s0, v2 bitop3:0x36
	s_movk_i32 s0, 0x80
	v_bitop3_b32 v7, v1, s0, v2 bitop3:0x36
	s_movk_i32 s0, 0xa0
	v_bitop3_b32 v8, v1, s0, v2 bitop3:0x36
	s_movk_i32 s0, 0xc0
	v_bitop3_b32 v9, v1, s0, v2 bitop3:0x36
	s_movk_i32 s0, 0xe0
	v_add_f32_e32 v208, 0x3ef1014c, v0
	v_lshlrev_b32_e32 v0, 3, v210
	v_or_b32_e32 v3, v1, v2
	v_bitop3_b32 v4, v1, 32, v2 bitop3:0x36
	v_bitop3_b32 v5, v1, 64, v2 bitop3:0x36
	v_bitop3_b32 v1, v1, s0, v2 bitop3:0x36
	v_bfe_u32 v2, v207, 2, 2
	v_lshrrev_b32_e32 v13, 3, v207
	v_bfe_u32 v14, v207, 1, 1
	v_or_b32_e32 v10, v0, v2
	v_lshlrev_b32_e32 v2, 2, v2
	v_lshlrev_b32_e32 v11, 1, v210
	v_and_or_b32 v13, v13, 2, v14
	v_lshlrev_b32_e32 v14, 3, v207
	v_bitop3_b32 v15, v11, v13, v2 bitop3:0x36
	v_or_b32_e32 v12, v11, v2
	v_and_b32_e32 v14, 8, v14
	v_lshl_add_u32 v10, v10, 8, 0
	v_lshlrev_b32_e32 v15, 4, v15
	v_add3_u32 v215, v10, v15, v14
	v_bitop3_b32 v15, v12, v13, 1 bitop3:0x36
	v_lshlrev_b32_e32 v15, 4, v15
	v_add3_u32 v217, v10, v15, v14
	v_or_b32_e32 v15, 4, v13
	v_bitop3_b32 v16, v11, v15, v2 bitop3:0x36
	v_bitop3_b32 v15, v12, v15, 1 bitop3:0x36
	v_lshlrev_b32_e32 v15, 4, v15
	v_lshlrev_b32_e32 v16, 4, v16
	v_add3_u32 v221, v10, v15, v14
	v_or_b32_e32 v15, 8, v13
	v_or_b32_e32 v13, 12, v13
	v_add3_u32 v219, v10, v16, v14
	v_bitop3_b32 v16, v11, v15, v2 bitop3:0x36
	v_bitop3_b32 v2, v11, v13, v2 bitop3:0x36
	v_lshlrev_b32_e32 v2, 4, v2
	v_add3_u32 v227, v10, v2, v14
	v_bitop3_b32 v2, v12, v13, 1 bitop3:0x36
	v_lshlrev_b32_e32 v2, 4, v2
	v_and_b32_e32 v209, 31, v207
	v_add3_u32 v229, v10, v2, v14
	v_or_b32_e32 v2, 2, v0
	v_cmp_gt_u32_e64 s[6:7], v2, v209
	v_or_b32_e32 v2, 3, v0
	v_cmp_gt_u32_e64 s[8:9], v2, v209
	v_or_b32_e32 v2, 4, v0
	v_cmp_gt_u32_e64 s[10:11], v2, v209
	v_or_b32_e32 v2, 5, v0
	v_cmp_gt_u32_e64 s[12:13], v2, v209
	v_or_b32_e32 v2, 6, v0
	v_cmp_gt_u32_e64 s[14:15], v2, v209
	v_or_b32_e32 v2, 7, v0
	v_cmp_gt_u32_e64 s[16:17], v2, v209
	v_or_b32_e32 v2, 16, v0
	v_cmp_gt_u32_e64 s[18:19], v2, v209
	v_or_b32_e32 v2, 17, v0
	v_cmp_gt_u32_e64 s[20:21], v2, v209
	v_or_b32_e32 v2, 18, v0
	s_add_i32 s2, 0, 0x18000
	v_cmp_gt_u32_e64 s[22:23], v2, v209
	v_or_b32_e32 v2, 19, v0
	v_bitop3_b32 v15, v12, v15, 1 bitop3:0x36
	v_cmp_gt_u32_e64 s[24:25], v2, v209
	v_or_b32_e32 v2, 20, v0
	s_add_u32 s48, s60, 0xe000000
	v_lshlrev_b32_e32 v16, 4, v16
	v_lshlrev_b32_e32 v15, 4, v15
	v_cmp_gt_u32_e64 s[26:27], v2, v209
	v_or_b32_e32 v2, 21, v0
	s_addc_u32 s49, s61, 0
	v_lshl_add_u32 v211, v206, 4, s2
	v_lshrrev_b32_e32 v212, 4, v206
	v_add3_u32 v223, v10, v16, v14
	v_add3_u32 v225, v10, v15, v14
	v_cmp_gt_u32_e64 s[2:3], v0, v209
	v_cmp_lt_u32_e64 s[4:5], v0, v209
	v_cmp_gt_u32_e64 s[28:29], v2, v209
	v_or_b32_e32 v2, 22, v0
	v_or_b32_e32 v0, 23, v0
	s_add_u32 s54, s60, 0x12000000
	v_and_b32_e32 v213, 15, v207
	v_lshlrev_b32_e32 v214, 2, v212
	v_add_u32_e32 v216, 0xc000, v215
	v_add_u32_e32 v218, 0xc400, v217
	v_add_u32_e32 v220, 0xc000, v219
	v_add_u32_e32 v222, 0xc400, v221
	v_add_u32_e32 v224, 0xc000, v223
	v_add_u32_e32 v226, 0xc400, v225
	v_add_u32_e32 v228, 0xc000, v227
	v_add_u32_e32 v230, 0xc400, v229
	v_cmp_gt_u32_e64 s[30:31], v2, v209
	v_cmp_gt_u32_e64 s[34:35], v0, v209
	s_addc_u32 s55, s61, 0
	v_sub_u32_e32 v231, 0, v209
	s_movk_i32 s70, 0xf0
	s_add_i32 s71, 0, 0x10000
	s_add_i32 s72, 0, 0x14000
	v_mov_b32_e32 v232, 0x358637bd
	v_mov_b32_e32 v233, 0x42800000
	v_add_u32_e32 v234, 0, v8
	v_add_u32_e32 v235, 0, v7
	v_add_u32_e32 v236, 0, v4
	v_add_u32_e32 v237, 0, v3
	v_add_u32_e32 v238, 0, v1
	v_add_u32_e32 v239, 0, v9
	v_add_u32_e32 v240, 0, v6
	v_add_u32_e32 v241, 0, v5
	v_mov_b32_e32 v242, 0xff800000
	v_mov_b32_e32 v181, 0x41000000
	s_and_b32 s73, s33, 7
	s_lshl_b32 s73, s73, 4
	s_lshr_b32 s99, s33, 3
	s_and_b32 s100, s99, 15
	s_add_i32 s73, s73, s100
	s_lshr_b32 s100, s99, 4
	s_lshl_b32 s100, s100, 7
	s_add_i32 s73, s73, s100
	s_cmp_lg_u32 s101, 0
	s_cselect_b32 s73, s73, s33
	s_branch .LBB0_736

.LBB0_913:
	s_cmp_lt_i32 s62, 9
	s_cselect_b64 s[0:1], -1, 0
	s_and_b64 s[0:1], s[0:1], s[2:3]
	s_andn2_b64 vcc, exec, s[0:1]
	s_cbranch_vccnz .LBB0_929
	s_and_b32 s0, s33, 7
	s_lshl_b32 s0, s0, 12
	s_lshr_b32 s98, s33, 3
	s_lshl_b32 s98, s98, 3
	s_add_i32 s0, s0, s98
	s_and_b32 s98, s33, 7
	s_add_i32 s98, s98, 1
	s_lshl_b32 s98, s98, 12
	s_lshl_b32 s99, s33, 3
	s_cmp_lg_u32 s101, 0
	s_cselect_b32 s0, s0, s99
	s_cselect_b32 s98, s98, 0x8000
	v_readlane_b32 s1, v243, 6
	s_add_i32 s6, s1, s0
	s_cmp_ge_i32 s6, s98
	s_cbranch_scc1 .LBB0_929
	v_lshlrev_b32_e32 v64, 4, v206
	s_waitcnt lgkmcnt(0)
	global_load_dwordx4 v[0:3], v64, s[56:57]
	global_load_dwordx4 v[4:7], v64, s[56:57] offset:1024
	global_load_dwordx4 v[8:11], v64, s[56:57] offset:2048
	global_load_dwordx4 v[12:15], v64, s[56:57] offset:3072
	v_mov_b32_e32 v65, 0
	v_lshlrev_b32_e32 v16, 3, v206
	v_mov_b32_e32 v17, v65
	v_lshl_add_u64 v[66:67], s[42:43], 0, v[16:17]
	v_lshl_add_u64 v[68:69], s[44:45], 0, v[16:17]
	v_mbcnt_lo_u32_b32 v16, -1, 0
	v_mbcnt_hi_u32_b32 v16, -1, v16
	v_and_b32_e32 v17, 64, v16
	v_add_u32_e32 v17, 64, v17
	v_xor_b32_e32 v18, 1, v16
	v_cmp_lt_i32_e32 vcc, v18, v17
	s_add_u32 s18, s60, 0x1500000
	s_addc_u32 s19, s61, 0
	v_cndmask_b32_e32 v18, v16, v18, vcc
	v_lshlrev_b32_e32 v136, 2, v18
	v_xor_b32_e32 v18, 2, v16
	v_cmp_lt_i32_e32 vcc, v18, v17
	s_lshl_b32 s0, s64, 3
	s_cmp_lg_u32 s101, 0
	s_cselect_b32 s0, 0x100, s0
	s_ashr_i32 s1, s0, 31
	v_cndmask_b32_e32 v18, v16, v18, vcc
	v_lshlrev_b32_e32 v137, 2, v18
	v_xor_b32_e32 v18, 4, v16
	v_cmp_lt_i32_e32 vcc, v18, v17
	v_lshl_add_u64 v[70:71], s[58:59], 0, v[64:65]
	s_lshl_b32 s20, s64, 4
	s_cmp_lg_u32 s101, 0
	s_cselect_b32 s20, 0x200, s20
	v_cndmask_b32_e32 v18, v16, v18, vcc
	v_lshlrev_b32_e32 v138, 2, v18
	v_xor_b32_e32 v18, 8, v16
	v_cmp_lt_i32_e32 vcc, v18, v17
	s_mul_i32 s21, s64, 24
	s_cmp_lg_u32 s101, 0
	s_cselect_b32 s21, 0x300, s21
	s_lshl_b64 s[2:3], s[0:1], 2
	v_cndmask_b32_e32 v18, v16, v18, vcc
	v_lshlrev_b32_e32 v139, 2, v18
	v_xor_b32_e32 v18, 16, v16
	v_cmp_lt_i32_e32 vcc, v18, v17
	v_mov_b32_e32 v142, 0x358637bd
	s_mov_b32 s1, 0x800000
	v_cndmask_b32_e32 v18, v16, v18, vcc
	v_lshlrev_b32_e32 v140, 2, v18
	v_xor_b32_e32 v18, 32, v16
	v_cmp_lt_i32_e32 vcc, v18, v17
	s_nop 1
	v_cndmask_b32_e32 v16, v16, v18, vcc
	v_lshlrev_b32_e32 v141, 2, v16
	s_branch .LBB0_917
